# w_in-gap workgroups take 13 instead of 11 conversion jobs of the current layer's ffn-up slice; phase 0 converts 600 fewer jobs
# baseline (speedup 1.0000x reference)
; #define LAS __attribute__((address_space(3)))
; __device__ __forceinline__ int opaque_tid() { int t = threadIdx.x; asm volatile("" : "+v"(t)); return t; }
; template <bool PREPMAP> __device__ __forceinline__ int cvt_map(int q) {
;     if (!PREPMAP) return q;
;     constexpr int NL = (NLAYER - 1) * GAP_PRE;
;     if (q >= NL) return q - NL;
;     return (1 + q / GAP_PRE) * CT_LAYER + q % GAP_PRE;
; }
; template <bool PREPMAP>
; __device__ __forceinline__ void convert_jobs(const Params& p, int job0, int job_end, int stride, LAS unsigned char* lds) {
;     if (job0 >= job_end) return;
;     const int tid = opaque_tid();
;     int job = job0;
;     CvtJob cur = cvt_decode(p, cvt_map<PREPMAP>(job));
.LBB0_11:
	s_or_b64 exec, exec, s[4:5]
	s_mov_b32 s24, s80
	s_cmpk_gt_i32 s80, 0x133a
	s_cbranch_scc1 .LBB0_197
	v_mov_b32_e32 v36, v210
	s_cmpk_lt_i32 s80, 0xd7a
	s_cbranch_scc0 .LBB0_14
	s_mul_hi_i32 s4, s80, 0x38fce3
	s_lshr_b32 s5, s4, 31
	s_ashr_i32 s4, s4, 0
	s_add_i32 s4, s4, s5
	s_mul_i32 s5, s4, 0xc50
	s_mulk_i32 s4, 0x47e
	s_sub_i32 s4, s80, s4
	s_add_i32 s4, s4, s5
	s_add_i32 s7, s4, 0xc50
	s_cbranch_execz .LBB0_15
	s_branch .LBB0_16
.LBB0_14:
.LBB0_15:
	s_add_i32 s7, s80, 0xfffff286
	s_add_i32 s4, s7, 0x3cf
	s_cmpk_lt_i32 s7, 0x47e
	s_cselect_b32 s7, s7, s4

; template <bool PREPMAP> __device__ __forceinline__ int cvt_map(int q) {
;     if (!PREPMAP) return q;
;     constexpr int NL = (NLAYER - 1) * GAP_PRE;
;     if (q >= NL) return q - NL;
;     return (1 + q / GAP_PRE) * CT_LAYER + q % GAP_PRE;
; }
; template <bool PREPMAP>
; __device__ __forceinline__ void convert_jobs(const Params& p, int job0, int job_end, int stride, LAS unsigned char* lds) {
;     ...
;     for (;;) {
;         const int nj = job + stride; const bool more = nj < job_end;
;         CvtJob nxt = cur; f32x4 v2[8]; float gk2[8];
;         if (more) { nxt = cvt_decode(p, cvt_map<PREPMAP>(nj)); cvt_load(nxt, tid, v2, gk2); }
.LBB0_106:
	s_load_dwordx2 s[4:5], s[0:1], 0xb0
	s_mov_b64 s[48:49], s[34:35]
	s_mov_b32 s66, s25
	s_mov_b32 s56, s36
	s_mov_b32 s67, s33
	s_waitcnt lgkmcnt(0)
	s_add_i32 s65, s24, s4
	s_cmpk_lt_i32 s65, 0x133b
	s_cselect_b64 s[46:47], -1, 0
	s_cmpk_gt_i32 s65, 0x133a
	s_cselect_b64 s[44:45], -1, 0
	s_and_b64 vcc, exec, s[44:45]
	s_cbranch_vccnz .LBB0_194
	s_cmpk_lt_i32 s65, 0xd7a
	s_mov_b64 s[4:5], -1
	s_cbranch_scc0 .LBB0_109
	s_mul_hi_i32 s4, s65, 0x38fce3
	s_lshr_b32 s5, s4, 31
	s_ashr_i32 s4, s4, 0
	s_add_i32 s4, s4, s5
	s_mul_i32 s5, s4, 0xc50
	s_mulk_i32 s4, 0x47e
	s_sub_i32 s4, s65, s4
	s_add_i32 s4, s4, s5
	s_add_i32 s7, s4, 0xc50
	s_mov_b64 s[4:5], 0
.LBB0_109:
	s_andn2_b64 vcc, exec, s[4:5]
	s_cbranch_vccnz .LBB0_111
	s_add_i32 s7, s65, 0xfffff286
	s_add_i32 s4, s7, 0x3cf
	s_cmpk_lt_i32 s7, 0x47e
	s_cselect_b32 s7, s7, s4

; #define LAS __attribute__((address_space(3)))
; __device__ __forceinline__ unsigned xb_ld(unsigned* p)              { return __hip_atomic_load(p, __ATOMIC_RELAXED, __HIP_MEMORY_SCOPE_AGENT); }
; __device__ __forceinline__ void xcd_barrier_complete(unsigned* bar, unsigned x, unsigned& nloc, unsigned& nx) {
;     const unsigned G = gridDim.x * gridDim.y * gridDim.z;
;     unsigned sum, cnt, mine, sp = 0u;
;     for (;;) {
;         sum = 0u; cnt = 0u; mine = 0u;
; #pragma unroll
;         for (unsigned j = 0; j < 16; ++j) { const unsigned c = xb_ld(&bar[XB_XCNT(j)]); sum += c; cnt += (c > 0u) ? 1u : 0u; mine = (j == x) ? c : mine; }
;         if (sum == G) break;
;         __builtin_amdgcn_s_sleep(1);
;         if ((++sp & 255u) == 0u) { if (xb_ld(&bar[XB_TMO])) break; if (sp > XB_SPIN_CAP) { atomicAdd(&bar[XB_TMO], 1u); break; } }
;     }
;     nloc = mine > 0u ? mine : 1u; nx = cnt > 0u ? cnt : 1u;
; __device__ __forceinline__ void convert_gap(const Params& p, int layer, int nwg, int base, int per, LAS unsigned char* lds) {
;     if (layer + 1 >= NLAYER) return;
;     const int G = gridDim.x, c = blockIdx.x, rem = nwg % G;
;     const int limit = base == GAP_PRE ? GAP_BASE6 : CT_LAYER;
;     if (rem == 0) { __syncthreads(); convert_jobs<false>(p, (layer + 1) * CT_LAYER + base + c, (layer + 1) * CT_LAYER + limit, G, lds); return; }
;     if (c < rem) return;
;     const int slot = c - rem, nslots = G - rem;
;     int j0 = base + slot * per, j1 = j0 + per;
;     if (slot == nslots - 1 || j1 > limit) j1 = limit;
.LBB0_295:
	s_load_dwordx2 s[20:21], s[0:1], 0xb0
	s_lshl_b32 s4, s80, 9
	v_writelane_b32 v252, s4, 5
	s_mov_b32 s15, 0
	s_mov_b32 s31, s6
	s_waitcnt lgkmcnt(0)
	s_lshl_b32 s4, s20, 3
	s_and_b32 s4, s4, 0x3fffff8
	s_cmpk_gt_i32 s80, 0xff
	v_writelane_b32 v252, s4, 6
	s_cselect_b64 s[4:5], -1, 0
	v_writelane_b32 v252, s4, 7
	s_cmpk_lt_u32 s80, 0x1b0
	s_mov_b32 s86, 0xfff58000
	v_writelane_b32 v252, s5, 8
	s_cselect_b64 s[4:5], -1, 0
	v_writelane_b32 v252, s4, 9
	s_ashr_i32 s7, s20, 31
	s_lshl_b32 s30, s20, 9
	v_writelane_b32 v252, s5, 10
	s_and_b32 s4, s80, 7
	v_writelane_b32 v252, s4, 11
	s_bfe_u32 s4, s80, 0x50003
	v_writelane_b32 v252, s4, 12
	s_lshl_b32 s14, s4, 9
	v_writelane_b32 v252, s14, 13
	s_ashr_i32 s4, s80, 31
	s_mov_b32 s88, 0xfffe0000
	v_writelane_b32 v252, s15, 14
	v_writelane_b32 v252, s4, 15
	s_lshr_b32 s4, s4, 29
	s_add_i32 s5, s80, s4
	s_ashr_i32 s4, s5, 3
	s_and_b32 s5, s5, -8
	s_sub_i32 s5, s80, s5
	s_lshl_b32 s6, s5, 5
	s_cmpk_lt_i32 s80, 0x5ac
	v_writelane_b32 v252, s7, 16
	s_cselect_b64 s[8:9], -1, 0
	v_writelane_b32 v252, s8, 17
	s_mul_i32 s7, s5, 0xb5
	s_add_i32 s7, s7, 4
	v_writelane_b32 v252, s9, 18
	s_add_i32 s8, s80, 0x84d
	v_writelane_b32 v252, s8, 19
	s_and_b32 s8, s80, 0x7fffff80
	s_cmpk_eq_i32 s8, 0x100
	s_cselect_b64 s[8:9], -1, 0
	v_writelane_b32 v252, s8, 20
	v_mov_b32_e32 v211, 0x419c8000
	v_mov_b32_e32 v212, 0x358637bd
	v_writelane_b32 v252, s9, 21
	s_bfe_u32 s8, s80, 0x40003
	s_lshl_b32 s14, s8, 8
	v_writelane_b32 v252, s8, 22
	s_add_u32 s8, s26, 0x419c8800
	s_addc_u32 s9, s27, 0
	s_add_u32 s22, s26, 0x419c8a00
	v_writelane_b32 v252, s8, 23
	s_addc_u32 s23, s27, 0
	v_mov_b32_e32 v213, 1
	v_writelane_b32 v252, s9, 24
	s_add_u32 s8, s26, 0x419c8b00
	s_addc_u32 s9, s27, 0
	v_writelane_b32 v252, s8, 25
	v_mov_b32_e32 v214, 0x3ecc95a3
	v_mov_b64_e32 v[216:217], 0xff
	v_writelane_b32 v252, s9, 26
	s_add_u32 s8, s26, 0x419c8c00
	s_addc_u32 s9, s27, 0
	v_writelane_b32 v252, s8, 27
	v_mov_b32_e32 v218, 0xc50
	v_mov_b32_e32 v219, 0xff800000
	v_writelane_b32 v252, s9, 28
	s_add_u32 s8, s26, 0x419c8d00
	s_addc_u32 s9, s27, 0
	v_writelane_b32 v252, s8, 29
	v_mov_b32_e32 v220, 0x60
	v_mov_b32_e32 v221, 0x7f800000
	v_writelane_b32 v252, s9, 30
	s_add_u32 s8, s26, 0x419c8e00
	s_addc_u32 s9, s27, 0
	v_writelane_b32 v252, s8, 31
	v_mov_b32_e32 v222, 0x7fc00000
	s_movk_i32 s81, 0x2a00
	v_writelane_b32 v252, s9, 32
	s_add_u32 s8, s26, 0x419c8f00
	s_addc_u32 s9, s27, 0
	v_writelane_b32 v252, s8, 33
	s_mov_b64 s[82:83], 0x40000
	s_mov_b64 s[84:85], 0x20000
	v_writelane_b32 v252, s9, 34
	s_add_u32 s8, s26, 0x419c9000
	s_addc_u32 s9, s27, 0
	v_writelane_b32 v252, s8, 35
	s_mov_b32 s87, -1
	s_mov_b32 s89, -1
	v_writelane_b32 v252, s9, 36
	s_add_u32 s8, s26, 0x419c9100
	s_addc_u32 s9, s27, 0
	v_writelane_b32 v252, s8, 37
	s_nop 1
	v_writelane_b32 v252, s9, 38
	s_add_u32 s8, s26, 0x419c9200
	s_addc_u32 s9, s27, 0
	v_writelane_b32 v252, s8, 39
	s_nop 1
	v_writelane_b32 v252, s9, 40
	s_add_u32 s8, s26, 0x419c9300
	s_addc_u32 s9, s27, 0
	v_writelane_b32 v252, s8, 41
	s_nop 1
	v_writelane_b32 v252, s9, 42
	s_add_u32 s8, s26, 0x419c9400
	s_addc_u32 s9, s27, 0
	v_writelane_b32 v252, s8, 43
	s_nop 1
	v_writelane_b32 v252, s9, 44
	s_add_u32 s8, s26, 0x419c9500
	s_addc_u32 s9, s27, 0
	v_writelane_b32 v252, s8, 45
	s_nop 1
	v_writelane_b32 v252, s9, 46
	s_add_u32 s8, s26, 0x419c9600
	s_addc_u32 s9, s27, 0
	v_writelane_b32 v252, s8, 47
	s_nop 1
	v_writelane_b32 v252, s9, 48
	s_add_u32 s8, s26, 0x419c9700
	s_addc_u32 s9, s27, 0
	v_writelane_b32 v252, s8, 49
	s_nop 1
	v_writelane_b32 v252, s9, 50
	s_add_u32 s8, s26, 0x419c9800
	s_addc_u32 s9, s27, 0
	v_writelane_b32 v252, s8, 51
	s_nop 1
	v_writelane_b32 v252, s9, 52
	s_add_u32 s8, s26, 0x419c9900
	s_addc_u32 s9, s27, 0
	v_writelane_b32 v252, s8, 53
	s_cmp_eq_u32 s3, 15
	s_nop 0
	v_writelane_b32 v252, s9, 54
	s_cselect_b64 s[8:9], -1, 0
	v_writelane_b32 v252, s8, 55
	s_cmp_eq_u32 s3, 14
	s_nop 0
	v_writelane_b32 v252, s9, 56
	s_cselect_b64 s[8:9], -1, 0
	v_writelane_b32 v252, s8, 57
	s_cmp_eq_u32 s3, 13
	s_nop 0
	v_writelane_b32 v252, s9, 58
	s_cselect_b64 s[8:9], -1, 0
	v_writelane_b32 v252, s8, 59
	s_cmp_eq_u32 s3, 12
	s_nop 0
	v_writelane_b32 v252, s9, 60
	s_cselect_b64 s[8:9], -1, 0
	v_writelane_b32 v252, s8, 61
	s_cmp_eq_u32 s3, 11
	s_nop 0
	v_writelane_b32 v252, s9, 62
	s_cselect_b64 s[8:9], -1, 0
	v_writelane_b32 v252, s8, 63
	s_cmp_eq_u32 s3, 10
	s_nop 0
	v_writelane_b32 v253, s9, 0
	s_cselect_b64 s[8:9], -1, 0
	v_writelane_b32 v253, s8, 1
	s_cmp_eq_u32 s3, 9
	s_nop 0
	v_writelane_b32 v253, s9, 2
	s_cselect_b64 s[8:9], -1, 0
	v_writelane_b32 v253, s8, 3
	s_cmp_eq_u32 s3, 8
	s_nop 0
	v_writelane_b32 v253, s9, 4
	s_cselect_b64 s[8:9], -1, 0
	v_writelane_b32 v253, s8, 5
	s_cmp_eq_u32 s3, 7
	s_nop 0
	v_writelane_b32 v253, s9, 6
	s_cselect_b64 s[8:9], -1, 0
	v_writelane_b32 v253, s8, 7
	s_cmp_eq_u32 s3, 6
	s_nop 0
	v_writelane_b32 v253, s9, 8
	s_cselect_b64 s[8:9], -1, 0
	v_writelane_b32 v253, s8, 9
	s_cmp_eq_u32 s3, 5
	s_nop 0
	v_writelane_b32 v253, s9, 10
	s_cselect_b64 s[8:9], -1, 0
	v_writelane_b32 v253, s8, 11
	s_cmp_eq_u32 s3, 4
	s_nop 0
	v_writelane_b32 v253, s9, 12
	s_cselect_b64 s[8:9], -1, 0
	v_writelane_b32 v253, s8, 13
	s_cmp_eq_u32 s3, 3
	s_nop 0
	v_writelane_b32 v253, s9, 14
	s_cselect_b64 s[8:9], -1, 0
	v_writelane_b32 v253, s8, 15
	s_cmp_eq_u32 s3, 2
	s_nop 0
	v_writelane_b32 v253, s9, 16
	s_cselect_b64 s[8:9], -1, 0
	v_writelane_b32 v253, s8, 17
	s_cmp_eq_u32 s3, 1
	s_nop 0
	v_writelane_b32 v253, s9, 18
	s_cselect_b64 s[8:9], -1, 0
	v_writelane_b32 v253, s8, 19
	s_cmp_eq_u32 s3, 0
	s_nop 0
	v_writelane_b32 v253, s9, 20
	s_cselect_b64 s[8:9], -1, 0
	s_lshl_b32 s3, s3, 8
; #define LAS __attribute__((address_space(3)))
;     __device__ bool next(int i, Unit& u) const {
;         const long L = (long)i * G + c; if (L >= nwg) return false;
;         int wgid = (int)L; { const int q = nwg / NXCD, r = nwg % NXCD, xcd = wgid % NXCD, off = wgid / NXCD; wgid = (xcd < r ? xcd * (q + 1) : r * (q + 1) + (xcd - r) * q) + off; }
;         const int nig = WGM * nN, gid = wgid / nig, fm = gid * WGM, gsz = (nM - fm) < WGM ? (nM - fm) : WGM;
;         u.pm = fm + ((wgid % nig) % gsz); u.pn = (wgid % nig) / gsz; u.k0t = 0; u.nt = ntk; u.part = -1; return true;
;     }
; __device__ __forceinline__ void convert_gap(const Params& p, int layer, int nwg, int base, int per, LAS unsigned char* lds) {
;     if (layer + 1 >= NLAYER) return;
;     const int G = gridDim.x, c = blockIdx.x, rem = nwg % G;
;     const int limit = base == GAP_PRE ? GAP_BASE6 : CT_LAYER;
;     if (rem == 0) { __syncthreads(); convert_jobs<false>(p, (layer + 1) * CT_LAYER + base + c, (layer + 1) * CT_LAYER + limit, G, lds); return; }
;     if (c < rem) return;
;     const int slot = c - rem, nslots = G - rem;
;     int j0 = base + slot * per, j1 = j0 + per;
;     if (slot == nslots - 1 || j1 > limit) j1 = limit;
	v_writelane_b32 v253, s8, 21
	s_add_u32 s3, s28, s3
	s_nop 0
	v_writelane_b32 v253, s9, 22
	s_addc_u32 s8, s29, 0
	s_add_u32 s10, s3, 0x1400
	s_addc_u32 s11, s8, 0
	v_writelane_b32 v253, s10, 23
	s_nop 1
	v_writelane_b32 v253, s11, 24
	s_add_u32 s10, s3, 0x2400
	s_addc_u32 s11, s8, 0
	v_writelane_b32 v253, s10, 25
	s_add_u32 s8, s26, 0x419cba00
	s_addc_u32 s9, s27, 0
	v_writelane_b32 v253, s11, 26
	v_writelane_b32 v253, s8, 27
	s_mul_i32 s3, s5, 57
	s_nop 0
	v_writelane_b32 v253, s9, 28
	s_add_u32 s8, s26, 0x419cbb00
	s_addc_u32 s9, s27, 0
	v_writelane_b32 v253, s8, 29
	s_cmpk_lt_i32 s80, 0x1ce
	s_mov_b64 s[26:27], 0x80
	v_writelane_b32 v253, s9, 30
	s_cselect_b64 s[8:9], -1, 0
	v_writelane_b32 v253, s8, 31
	s_nop 1
	v_writelane_b32 v253, s9, 32
	s_add_i32 s8, s3, 6
	s_add_i32 s3, s20, -8
	s_cmp_ge_i32 s80, s3
	s_cselect_b64 s[10:11], -1, 0
	s_not_b32 s3, s80
	s_add_i32 s3, s20, s3
	v_writelane_b32 v253, s10, 33
	s_cmpk_lt_i32 s80, 0x2b5
	s_mul_i32 s9, s5, 0x56
	v_writelane_b32 v253, s11, 34
	s_cselect_b64 s[10:11], -1, 0
	v_writelane_b32 v253, s10, 35
	s_add_i32 s9, s9, 5
	s_nop 0
	v_writelane_b32 v253, s11, 36
	s_add_i32 s10, s80, 0x47e
	v_writelane_b32 v253, s10, 37
	s_cmp_lt_i32 s5, 0
	s_mul_i32 s10, s5, 33
	s_cselect_b32 s6, s10, s6
	s_add_i32 s6, s6, s4
	s_ashr_i32 s10, s6, 31
	s_lshr_b32 s10, s10, 26
	s_add_i32 s10, s6, s10
	s_and_b32 s11, s10, 0xffc0
	s_sub_i32 s6, s6, s11
	s_bfe_i32 s11, s6, 0x80000
	s_bfe_u32 s11, s11, 0x3000c
	s_add_i32 s11, s6, s11
	s_and_b32 s12, s11, 0xf8
	s_sub_i32 s6, s6, s12
	s_ashr_i32 s10, s10, 6
	s_lshl_b32 s10, s10, 3
	s_sext_i32_i8 s6, s6
	s_add_i32 s6, s6, s10
	s_bfe_i32 s10, s11, 0x80000
	s_sext_i32_i16 s10, s10
	s_ashr_i32 s10, s10, 3
	v_writelane_b32 v253, s10, 38
	s_add_i32 s6, s6, 1
	v_writelane_b32 v253, s6, 39
	s_cmp_lt_i32 s5, 4
	s_mul_i32 s6, s5, 0xb6
	s_cselect_b32 s6, s6, s7
	s_add_i32 s6, s6, s4
	s_mul_hi_i32 s7, s6, 0x2e8ba2e9
	s_lshr_b32 s10, s7, 31
	s_ashr_i32 s7, s7, 6
	s_add_i32 s7, s7, s10
	s_mul_i32 s10, s7, 0x160
	s_lshl_b32 s7, s7, 3
	s_sub_i32 s10, s6, s10
	s_sub_i32 s6, 33, s7
	s_min_u32 s11, s6, 8
	s_cmp_lt_i32 s5, 6
	s_mul_i32 s6, s5, 58
	s_cselect_b32 s6, s6, s8
	s_add_i32 s6, s6, s4
	s_mul_hi_i32 s8, s6, 0x92492493
	s_add_i32 s8, s8, s6
	s_lshr_b32 s12, s8, 31
	s_ashr_i32 s8, s8, 6
	s_add_i32 s8, s8, s12
	s_mul_i32 s12, s8, 0x70
	s_lshl_b32 s8, s8, 3
	s_sub_i32 s12, s6, s12
	s_sub_i32 s6, 33, s8
	s_min_u32 s13, s6, 8
	s_cmp_lt_i32 s5, 5
	s_mulk_i32 s5, 0x57
	s_cselect_b32 s5, s5, s9
	v_cvt_f32_ubyte0_e32 v1, s11
	s_add_i32 s5, s5, s4
	v_cvt_f32_i32_e32 v0, s10
	v_rcp_iflag_f32_e32 v2, v1
	s_mul_hi_i32 s4, s5, 0x30c30c31
	s_lshr_b32 s6, s4, 31
	s_ashr_i32 s4, s4, 5
	s_add_i32 s4, s4, s6
	s_lshl_b32 s16, s4, 3
	v_mul_f32_e32 v2, v0, v2
	s_mul_i32 s6, s4, 0xa8
	s_sub_i32 s4, 33, s16
	v_trunc_f32_e32 v2, v2
	s_min_u32 s17, s4, 8
	s_ashr_i32 s4, s10, 30
	v_fma_f32 v0, -v2, v1, v0
	s_sub_i32 s9, s5, s6
	s_or_b32 s6, s4, 1
	v_cmp_ge_f32_e64 s[4:5], |v0|, v1
	v_cvt_i32_f32_e32 v0, v2
	s_and_b64 s[4:5], s[4:5], exec
	s_cselect_b32 s4, s6, 0
	v_cvt_f32_ubyte0_e32 v1, s13
	v_readfirstlane_b32 s5, v0
	s_add_i32 s6, s5, s4
	s_mul_i32 s4, s6, s11
	s_sub_i32 s4, s10, s4
	s_abs_i32 s10, s20
	v_cvt_f32_u32_e32 v0, s10
	s_sub_i32 s5, 0, s10
	s_sext_i32_i16 s4, s4
	s_add_i32 s24, s7, s4
	v_rcp_iflag_f32_e32 v0, v0
	s_mov_b32 s18, s24
	s_ashr_i32 s25, s24, 31
	v_rcp_iflag_f32_e32 v2, v1
	v_mul_f32_e32 v0, 0x4f7ffffe, v0
	v_cvt_u32_f32_e32 v0, v0
	s_nop 0
	v_readfirstlane_b32 s11, v0
	s_mul_i32 s5, s5, s11
	s_mul_hi_u32 s5, s11, s5
	s_add_i32 s11, s11, s5
	s_bfe_i64 s[4:5], s[6:7], 0x100000
	s_lshl_b64 s[4:5], s[4:5], 20
	v_writelane_b32 v253, s4, 40
	v_cvt_f32_i32_e32 v0, s12
	v_mul_f32_e32 v2, v0, v2
	v_writelane_b32 v253, s5, 41
	s_mul_hi_u32 s4, s11, 0x5ac
	s_mul_i32 s4, s4, s10
	s_sub_i32 s4, 0x5ac, s4
	v_writelane_b32 v253, s18, 42
	s_sub_i32 s5, s4, s10
	v_trunc_f32_e32 v2, v2
	v_writelane_b32 v253, s19, 43
	s_lshl_b64 s[18:19], s[24:25], 20
	s_cmp_ge_u32 s4, s10
	s_cselect_b32 s4, s5, s4
	s_sub_i32 s5, s4, s10
	s_cmp_ge_u32 s4, s10
	s_cselect_b32 s4, s5, s4
	v_writelane_b32 v253, s18, 44
	s_cmp_lg_u32 s4, 0
	v_fma_f32 v0, -v2, v1, v0
	v_writelane_b32 v253, s19, 45
	s_cselect_b64 s[18:19], -1, 0
	v_writelane_b32 v253, s18, 46
	s_cmp_ge_i32 s80, s4
	s_nop 0
	v_writelane_b32 v253, s19, 47
	s_cselect_b64 s[18:19], -1, 0
	s_sub_i32 s5, s80, s4
; #define LAS __attribute__((address_space(3)))
; __device__ __forceinline__ void convert_gap(const Params& p, int layer, int nwg, int base, int per, LAS unsigned char* lds) {
;     if (layer + 1 >= NLAYER) return;
;     const int G = gridDim.x, c = blockIdx.x, rem = nwg % G;
;     const int limit = base == GAP_PRE ? GAP_BASE6 : CT_LAYER;
;     if (rem == 0) { __syncthreads(); convert_jobs<false>(p, (layer + 1) * CT_LAYER + base + c, (layer + 1) * CT_LAYER + limit, G, lds); return; }
;     if (c < rem) return;
;     const int slot = c - rem, nslots = G - rem;
;     int j0 = base + slot * per, j1 = j0 + per;
;     if (slot == nslots - 1 || j1 > limit) j1 = limit;
;     if (j0 > limit) j0 = limit;
;     __syncthreads();
;     convert_jobs<false>(p, (layer + 1) * CT_LAYER + j0, (layer + 1) * CT_LAYER + j1, 1, lds);
	v_writelane_b32 v253, s18, 48
	s_mul_i32 s7, s5, 13
	s_not_b32 s4, s4
	v_writelane_b32 v253, s19, 49
	s_min_u32 s18, s7, 0x3f6
	s_add_i32 s4, s20, s4
	s_addk_i32 s18, 0x85a
	s_cmp_lg_u32 s5, s4
	s_cselect_b32 s5, s18, 0xc50
	s_min_u32 s4, s7, 0x403
	s_addk_i32 s4, 0x84d
	v_writelane_b32 v253, s5, 50
	s_cmp_lt_u32 s4, s5
	v_writelane_b32 v253, s4, 51
	s_cselect_b64 s[4:5], -1, 0
	v_writelane_b32 v253, s4, 52
	s_nop 1
	v_writelane_b32 v253, s5, 53
	s_ashr_i32 s4, s12, 30
	s_or_b32 s7, s4, 1
	v_cmp_ge_f32_e64 s[4:5], |v0|, v1
	v_cvt_i32_f32_e32 v0, v2
	s_and_b64 s[4:5], s[4:5], exec
	v_cvt_f32_ubyte0_e32 v1, s17
	s_cselect_b32 s4, s7, 0
	v_readfirstlane_b32 s5, v0
	v_cvt_f32_i32_e32 v0, s9
	v_rcp_iflag_f32_e32 v2, v1
	s_add_i32 s7, s5, s4
	s_mul_i32 s4, s7, s13
	s_sub_i32 s4, s12, s4
	s_sext_i32_i8 s4, s4
	v_mul_f32_e32 v2, v0, v2
	s_add_i32 s4, s8, s4
	v_trunc_f32_e32 v2, v2
	v_writelane_b32 v253, s4, 54
	s_ashr_i32 s4, s9, 30
	v_fma_f32 v0, -v2, v1, v0
	s_or_b32 s8, s4, 1
	v_cmp_ge_f32_e64 s[4:5], |v0|, v1
	v_cvt_i32_f32_e32 v0, v2
	s_and_b64 s[4:5], s[4:5], exec
	s_cselect_b32 s4, s8, 0
	v_mov_b32_e32 v1, 0
	v_readfirstlane_b32 s5, v0
	s_add_i32 s8, s5, s4
	s_mul_i32 s4, s8, s17
	s_sub_i32 s4, s9, s4
	s_sext_i32_i16 s4, s4
	s_add_i32 s4, s16, s4
	v_writelane_b32 v253, s4, 55
	s_mul_hi_u32 s4, s11, 0x2b5
	s_mul_i32 s4, s4, s10
	s_sub_i32 s4, 0x2b5, s4
	s_sub_i32 s5, s4, s10
	s_cmp_ge_u32 s4, s10
	s_cselect_b32 s4, s5, s4
	s_sub_i32 s5, s4, s10
	s_cmp_ge_u32 s4, s10
	s_cselect_b32 s4, s5, s4
	s_cmp_lg_u32 s4, 0
	s_cselect_b64 s[10:11], -1, 0
	v_writelane_b32 v253, s10, 56
	s_cmp_ge_i32 s80, s4
	v_mbcnt_lo_u32_b32 v0, -1, 0
	v_writelane_b32 v253, s11, 57
	s_cselect_b64 s[10:11], -1, 0
	s_sub_i32 s5, s80, s4
	v_writelane_b32 v253, s10, 58
	s_mul_i32 s9, s5, 13
	s_not_b32 s4, s4
	v_writelane_b32 v253, s11, 59
	s_min_u32 s10, s9, 0x3c2
	s_add_i32 s4, s20, s4
	s_addk_i32 s10, 0x48b
	s_cmp_lg_u32 s5, s4
	s_mul_i32 s4, s21, s20
	s_mul_i32 s47, s4, s2
	s_sext_i32_i16 s2, s6
	v_writelane_b32 v253, s2, 60
	s_sext_i32_i8 s2, s7
	v_writelane_b32 v253, s2, 61
	s_sext_i32_i16 s2, s8
	s_mul_hi_i32 s5, s3, 0x2100
	s_mul_i32 s4, s3, 0x2100
	v_writelane_b32 v253, s2, 62
	s_cselect_b32 s3, s10, 0x84d
	s_min_u32 s2, s9, 0x3cf
	s_addk_i32 s2, 0x47e
	v_writelane_b32 v254, s2, 0
	s_cmp_lt_u32 s2, s3
	v_writelane_b32 v254, s14, 1
	v_writelane_b32 v253, s3, 63
	s_cselect_b64 s[2:3], -1, 0
	v_writelane_b32 v254, s15, 2
	v_writelane_b32 v254, s2, 3
	s_and_b32 s14, s20, 0x7fffff
	s_lshl_b32 s25, s20, 12
	v_writelane_b32 v254, s3, 4
	s_lshl_b32 s2, s14, 4
	s_addk_i32 s2, 0xff
	v_writelane_b32 v254, s2, 5
	s_lshl_b64 s[2:3], s[4:5], 2
	v_writelane_b32 v254, s2, 6
	s_load_dwordx4 s[4:7], s[0:1], 0x98
	s_lshl_b64 s[0:1], s[14:15], 15
	v_writelane_b32 v254, s3, 7
	s_lshl_b32 s2, s80, 12
	v_writelane_b32 v254, s2, 8
	s_mul_i32 s2, s14, 0x15000
	v_writelane_b32 v254, s2, 9
	s_add_i32 s2, 0, 0x1fff0
	v_writelane_b32 v254, s2, 10
	s_add_i32 s2, 0, 0x10100
	v_writelane_b32 v254, s2, 11
	s_add_i32 s2, 0, 0x20004
	v_writelane_b32 v254, s2, 12
	s_waitcnt lgkmcnt(0)
	v_writelane_b32 v254, s4, 13
	v_mbcnt_hi_u32_b32 v215, -1, v0
	s_nop 0
	v_writelane_b32 v254, s5, 14
	v_writelane_b32 v254, s6, 15
	v_writelane_b32 v254, s7, 16
	v_writelane_b32 v254, s0, 17
	s_nop 1
	v_writelane_b32 v254, s1, 18
	s_lshl_b64 s[0:1], s[14:15], 16
	v_writelane_b32 v254, s0, 19
	s_nop 1
	v_writelane_b32 v254, s1, 20
	s_lshl_b64 s[0:1], s[14:15], 14
	v_writelane_b32 v254, s0, 21
	s_nop 1
	v_writelane_b32 v254, s1, 22
	v_writelane_b32 v254, s30, 23
	v_writelane_b32 v254, s47, 24
	v_writelane_b32 v254, s25, 25
	v_writelane_b32 v254, s22, 26
	s_nop 1
	v_writelane_b32 v254, s23, 27
	v_readlane_b32 s100, v254, 15
	v_readlane_b32 s101, v254, 16
	s_nop 1
	s_add_u32 s100, s100, 0x419c8500
	s_addc_u32 s101, s101, 0
	global_load_dwordx4 v[160:163], v1, s[100:101]
	global_load_dwordx4 v[164:167], v1, s[100:101] offset:16
	global_load_dwordx4 v[168:171], v1, s[100:101] offset:32
	global_load_dwordx4 v[172:175], v1, s[100:101] offset:48
	global_load_dwordx4 v[176:179], v1, s[100:101] offset:64
	global_load_dwordx4 v[180:183], v1, s[100:101] offset:80
	global_load_dwordx4 v[184:187], v1, s[100:101] offset:96
	global_load_dwordx4 v[188:191], v1, s[100:101] offset:112
	global_load_dwordx4 v[192:195], v1, s[100:101] offset:128
	global_load_dwordx2 v[196:197], v1, s[100:101] offset:144
	s_branch .LBB0_299
